# RG-LRU task prologue: all gate-weight loads of a pass in one group (one exposed load latency), second group's temporaries renamed to registers free in this stage
# baseline (speedup 1.0000x reference)
.LBB0_200:
	s_or_b64 exec, exec, s[80:81]
	v_readfirstlane_b32 s1, v0
	s_cmpk_gt_u32 s1, 0xff
	s_mov_b64 s[80:81], -1
	s_cbranch_scc1 .LBB0_195
	s_and_b32 s0, s45, 7
	s_lshl_b32 s0, s0, 8
	s_or_b32 s1, s1, s0
	s_bfe_u32 s0, s1, 0x30005
	s_lshl_b32 s20, s0, 8
	v_lshl_add_u64 v[24:25], v[144:145], 0, s[20:21]
	v_lshl_add_u64 v[20:21], v[146:147], 0, s[20:21]
	s_lshl_b32 s20, s0, 14
	v_lshl_add_u64 v[44:45], v[148:149], 0, s[20:21]
	v_mov_b32_e32 v161, v99
	v_lshl_add_u64 v[68:69], v[44:45], 0, v[160:161]
	global_load_dword v40, v[68:69], off offset:256
	global_load_dword v233, v[68:69], off
	global_load_dwordx4 v[0:3], v[24:25], off offset:16
	global_load_dwordx4 v[4:7], v[24:25], off
	global_load_dwordx4 v[8:11], v[24:25], off offset:2064
	global_load_dwordx4 v[12:15], v[24:25], off offset:2048
	v_add_co_u32_e32 v32, vcc, 0x1000, v24
	s_mov_b64 s[22:23], 0x1800
	v_lshl_add_u64 v[28:29], v[24:25], 0, s[54:55]
	v_lshl_add_u64 v[36:37], v[24:25], 0, s[22:23]
	v_addc_co_u32_e32 v33, vcc, 0, v25, vcc
	global_load_dwordx4 v[16:19], v[20:21], off offset:16
	s_nop 0
	global_load_dwordx4 v[20:23], v[20:21], off
	s_nop 0
	global_load_dwordx4 v[24:27], v[32:33], off
	s_nop 0
	global_load_dwordx4 v[28:31], v[28:29], off offset:16
	s_nop 0
	global_load_dwordx4 v[32:35], v[32:33], off offset:2048
	s_nop 0
	global_load_dwordx4 v[36:39], v[36:37], off offset:16
	v_mov_b32_e32 v163, v99
	v_lshl_add_u64 v[72:73], v[44:45], 0, v[162:163]
	v_lshl_add_u64 v[76:77], v[150:151], 0, s[20:21]
	v_lshl_add_u64 v[104:105], v[76:77], 0, v[160:161]
	v_lshl_add_u64 v[108:109], v[76:77], 0, v[162:163]
	s_lshl_b32 s26, s0, 6
	s_lshr_b32 s23, s1, 8
	s_lshl_b32 s1, s1, 7
	s_and_b32 s22, s1, 0xf80
	s_lshl_b32 s1, s23, 12
	s_or_b32 s20, s22, s1
	s_add_u32 s80, s20, -3
	s_addc_u32 s81, 0, -1
	v_cmp_gt_i32_e32 vcc, s22, v172
	v_mov_b32_e32 v110, v99
	v_mov_b32_e32 v111, v99
	global_load_dword v41, v[68:69], off offset:768
	global_load_dword v234, v[68:69], off offset:512
	global_load_dword v42, v[68:69], off offset:1280
	global_load_dword v235, v[68:69], off offset:1024
	global_load_dword v43, v[68:69], off offset:1792
	global_load_dword v236, v[68:69], off offset:1536
	global_load_dword v44, v[72:73], off offset:256
	global_load_dword v237, v[72:73], off
	global_load_dword v45, v[72:73], off offset:768
	global_load_dword v238, v[72:73], off offset:512
	global_load_dword v46, v[72:73], off offset:1280
	global_load_dword v239, v[72:73], off offset:1024
	global_load_dword v47, v[72:73], off offset:1792
	global_load_dword v240, v[72:73], off offset:1536
	global_load_dword v48, v[68:69], off offset:320
	global_load_dword v241, v[68:69], off offset:64
	global_load_dword v49, v[68:69], off offset:832
	global_load_dword v242, v[68:69], off offset:576
	global_load_dword v50, v[68:69], off offset:1344
	global_load_dword v243, v[68:69], off offset:1088
	global_load_dword v51, v[68:69], off offset:1856
	global_load_dword v244, v[68:69], off offset:1600
	global_load_dword v52, v[72:73], off offset:320
	global_load_dword v245, v[72:73], off offset:64
	global_load_dword v53, v[72:73], off offset:832
	global_load_dword v246, v[72:73], off offset:576
	global_load_dword v54, v[72:73], off offset:1344
	global_load_dword v247, v[72:73], off offset:1088
	global_load_dword v55, v[72:73], off offset:1856
	global_load_dword v248, v[72:73], off offset:1600
	global_load_dword v56, v[68:69], off offset:384
	global_load_dword v249, v[68:69], off offset:128
	global_load_dword v57, v[68:69], off offset:896
	global_load_dword v250, v[68:69], off offset:640
	global_load_dword v58, v[68:69], off offset:1408
	global_load_dword v251, v[68:69], off offset:1152
	global_load_dword v59, v[68:69], off offset:1920
	global_load_dword v252, v[68:69], off offset:1664
	global_load_dword v60, v[72:73], off offset:384
	global_load_dword v253, v[72:73], off offset:128
	global_load_dword v61, v[72:73], off offset:896
	global_load_dword v135, v[72:73], off offset:640
	global_load_dword v62, v[72:73], off offset:1408
	global_load_dword v136, v[72:73], off offset:1152
	global_load_dword v63, v[72:73], off offset:1920
	global_load_dword v137, v[72:73], off offset:1664
	global_load_dword v64, v[68:69], off offset:448
	global_load_dword v138, v[68:69], off offset:192
	global_load_dword v65, v[68:69], off offset:960
	global_load_dword v139, v[68:69], off offset:704
	global_load_dword v66, v[68:69], off offset:1472
	global_load_dword v140, v[68:69], off offset:1216
	global_load_dword v67, v[68:69], off offset:1984
	s_nop 0
	global_load_dword v141, v[68:69], off offset:1728
	global_load_dword v68, v[72:73], off offset:448
	global_load_dword v142, v[72:73], off offset:192
	global_load_dword v69, v[72:73], off offset:960
	global_load_dword v143, v[72:73], off offset:704
	global_load_dword v70, v[72:73], off offset:1472
	global_load_dword v165, v[72:73], off offset:1216
	global_load_dword v71, v[72:73], off offset:1984
	s_nop 0
	global_load_dword v168, v[72:73], off offset:1728
	global_load_dword v72, v[104:105], off offset:256
	global_load_dword v170, v[104:105], off
	global_load_dword v73, v[104:105], off offset:768
	global_load_dword v171, v[104:105], off offset:512
	global_load_dword v74, v[104:105], off offset:1280
	global_load_dword v222, v[104:105], off offset:1024
	global_load_dword v75, v[104:105], off offset:1792
	global_load_dword v223, v[104:105], off offset:1536
	global_load_dword v76, v[108:109], off offset:256
	global_load_dword v224, v[108:109], off
	global_load_dword v77, v[108:109], off offset:768
	global_load_dword v225, v[108:109], off offset:512
	global_load_dword v78, v[108:109], off offset:1280
	global_load_dword v226, v[108:109], off offset:1024
	global_load_dword v79, v[108:109], off offset:1792
	global_load_dword v227, v[108:109], off offset:1536
	global_load_dword v80, v[104:105], off offset:320
	global_load_dword v228, v[104:105], off offset:64
	global_load_dword v81, v[104:105], off offset:832
	global_load_dword v112, v[104:105], off offset:576
	global_load_dword v82, v[104:105], off offset:1344
	global_load_dword v113, v[104:105], off offset:1088
	global_load_dword v83, v[104:105], off offset:1856
	global_load_dword v114, v[104:105], off offset:1600
	global_load_dword v84, v[108:109], off offset:320
	global_load_dword v115, v[108:109], off offset:64
	global_load_dword v85, v[108:109], off offset:832
	global_load_dword v116, v[108:109], off offset:576
	global_load_dword v86, v[108:109], off offset:1344
	global_load_dword v117, v[108:109], off offset:1088
	global_load_dword v87, v[108:109], off offset:1856
	global_load_dword v118, v[108:109], off offset:1600
	global_load_dword v88, v[104:105], off offset:384
	global_load_dword v119, v[104:105], off offset:128
	global_load_dword v89, v[104:105], off offset:896
	global_load_dword v120, v[104:105], off offset:640
	global_load_dword v90, v[104:105], off offset:1408
	global_load_dword v121, v[104:105], off offset:1152
	global_load_dword v91, v[104:105], off offset:1920
	global_load_dword v122, v[104:105], off offset:1664
	global_load_dword v92, v[108:109], off offset:384
	global_load_dword v123, v[108:109], off offset:128
	global_load_dword v93, v[108:109], off offset:896
	global_load_dword v124, v[108:109], off offset:640
	global_load_dword v94, v[108:109], off offset:1408
	global_load_dword v125, v[108:109], off offset:1152
	global_load_dword v95, v[108:109], off offset:1920
	global_load_dword v126, v[108:109], off offset:1664
	global_load_dword v127, v[104:105], off offset:448
	global_load_dword v100, v[104:105], off offset:192
	global_load_dword v128, v[104:105], off offset:960
	global_load_dword v101, v[104:105], off offset:704
	global_load_dword v129, v[104:105], off offset:1472
	global_load_dword v102, v[104:105], off offset:1216
	global_load_dword v130, v[104:105], off offset:1984
	global_load_dword v103, v[104:105], off offset:1728
	global_load_dword v131, v[108:109], off offset:448
	global_load_dword v104, v[108:109], off offset:192
	global_load_dword v132, v[108:109], off offset:960
	global_load_dword v105, v[108:109], off offset:704
	global_load_dword v133, v[108:109], off offset:1472
	global_load_dword v106, v[108:109], off offset:1216
	global_load_dword v134, v[108:109], off offset:1984
	global_load_dword v107, v[108:109], off offset:1728
	v_or_b32_e32 v108, s26, v97
	v_lshlrev_b32_e32 v108, 2, v108
	v_mov_b32_e32 v109, v99
	s_waitcnt vmcnt(0)
	v_cvt_pk_bf16_f32 v40, v233, v40
	v_cvt_pk_bf16_f32 v41, v234, v41
	v_cvt_pk_bf16_f32 v42, v235, v42
	v_cvt_pk_bf16_f32 v43, v236, v43
	v_cvt_pk_bf16_f32 v44, v237, v44
	v_cvt_pk_bf16_f32 v45, v238, v45
	v_cvt_pk_bf16_f32 v46, v239, v46
	v_cvt_pk_bf16_f32 v47, v240, v47
	v_cvt_pk_bf16_f32 v48, v241, v48
	v_cvt_pk_bf16_f32 v49, v242, v49
	v_cvt_pk_bf16_f32 v50, v243, v50
	v_cvt_pk_bf16_f32 v51, v244, v51
	v_cvt_pk_bf16_f32 v52, v245, v52
	v_cvt_pk_bf16_f32 v53, v246, v53
	v_cvt_pk_bf16_f32 v54, v247, v54
	v_cvt_pk_bf16_f32 v55, v248, v55
	v_cvt_pk_bf16_f32 v56, v249, v56
	v_cvt_pk_bf16_f32 v57, v250, v57
	v_cvt_pk_bf16_f32 v58, v251, v58
	v_cvt_pk_bf16_f32 v59, v252, v59
	v_cvt_pk_bf16_f32 v60, v253, v60
	v_cvt_pk_bf16_f32 v61, v135, v61
	v_cvt_pk_bf16_f32 v62, v136, v62
	v_cvt_pk_bf16_f32 v63, v137, v63
	v_cvt_pk_bf16_f32 v64, v138, v64
	v_cvt_pk_bf16_f32 v65, v139, v65
	v_cvt_pk_bf16_f32 v66, v140, v66
	v_cvt_pk_bf16_f32 v67, v141, v67
	v_cvt_pk_bf16_f32 v68, v142, v68
	v_cvt_pk_bf16_f32 v69, v143, v69
	v_cvt_pk_bf16_f32 v70, v165, v70
	v_cvt_pk_bf16_f32 v71, v168, v71
	v_cvt_pk_bf16_f32 v72, v170, v72
	v_cvt_pk_bf16_f32 v73, v171, v73
	v_cvt_pk_bf16_f32 v74, v222, v74
	v_cvt_pk_bf16_f32 v75, v223, v75
	v_cvt_pk_bf16_f32 v76, v224, v76
	v_cvt_pk_bf16_f32 v77, v225, v77
	v_cvt_pk_bf16_f32 v78, v226, v78
	v_cvt_pk_bf16_f32 v79, v227, v79
	v_cvt_pk_bf16_f32 v80, v228, v80
	v_cvt_pk_bf16_f32 v81, v112, v81
	v_cvt_pk_bf16_f32 v82, v113, v82
	v_cvt_pk_bf16_f32 v83, v114, v83
	v_cvt_pk_bf16_f32 v84, v115, v84
	v_cvt_pk_bf16_f32 v85, v116, v85
	v_cvt_pk_bf16_f32 v86, v117, v86
	v_cvt_pk_bf16_f32 v87, v118, v87
	v_cvt_pk_bf16_f32 v88, v119, v88
	v_cvt_pk_bf16_f32 v89, v120, v89
	v_cvt_pk_bf16_f32 v90, v121, v90
	v_cvt_pk_bf16_f32 v91, v122, v91
	v_cvt_pk_bf16_f32 v92, v123, v92
	v_cvt_pk_bf16_f32 v93, v124, v93
	v_cvt_pk_bf16_f32 v94, v125, v94
	v_cvt_pk_bf16_f32 v95, v126, v95
	v_cvt_pk_bf16_f32 v100, v100, v127
	v_cvt_pk_bf16_f32 v101, v101, v128
	v_cvt_pk_bf16_f32 v102, v102, v129
	v_cvt_pk_bf16_f32 v103, v103, v130
	v_cvt_pk_bf16_f32 v104, v104, v131
	v_cvt_pk_bf16_f32 v105, v105, v132
	v_cvt_pk_bf16_f32 v106, v106, v133
	v_cvt_pk_bf16_f32 v107, v107, v134
	global_load_dword v161, v108, s[74:75]
	global_load_dword v163, v108, s[76:77]
	global_load_dword v181, v108, s[74:75] offset:64
	global_load_dword v188, v108, s[76:77] offset:64
	global_load_dword v189, v108, s[74:75] offset:128
	global_load_dword v190, v108, s[76:77] offset:128
	global_load_dword v191, v108, s[76:77] offset:192
	global_load_dword v192, v108, s[74:75] offset:192
	global_load_dword v123, v108, s[78:79]
	global_load_dword v122, v108, s[78:79] offset:64
	global_load_dword v121, v108, s[78:79] offset:128
	global_load_dword v120, v108, s[78:79] offset:192
	v_mov_b32_e32 v108, v99
	v_lshlrev_b32_e32 v98, 1, v96
	s_and_saveexec_b64 s[82:83], vcc
	s_cbranch_execz .LBB0_203
	v_lshl_add_u64 v[108:109], s[80:81], 0, v[152:153]
	v_mov_b64_e32 v[110:111], s[16:17]
	v_mad_u64_u32 v[110:111], s[42:43], v108, s99, v[110:111]
	v_mad_i32_i24 v111, v109, s99, v111
	s_lshl_b32 s20, s26, 1
	v_lshl_add_u64 v[108:109], v[110:111], 0, s[20:21]
	v_lshl_add_u64 v[108:109], v[108:109], 0, v[98:99]
	global_load_dwordx4 v[108:111], v[108:109], off offset:3072

.LBB0_250:
	s_bfe_u32 s0, s23, 0x30005
	s_lshl_b32 s20, s0, 8
	v_lshl_add_u64 v[24:25], v[96:97], 0, s[20:21]
	v_lshl_add_u64 v[20:21], v[152:153], 0, s[20:21]
	s_lshl_b32 s20, s0, 14
	v_lshl_add_u64 v[44:45], v[154:155], 0, s[20:21]
	v_mov_b32_e32 v173, v99
	v_lshl_add_u64 v[68:69], v[44:45], 0, v[172:173]
	global_load_dword v40, v[68:69], off offset:256
	global_load_dword v251, v[68:69], off
	global_load_dwordx4 v[0:3], v[24:25], off offset:16
	global_load_dwordx4 v[4:7], v[24:25], off
	global_load_dwordx4 v[8:11], v[24:25], off offset:2064
	global_load_dwordx4 v[12:15], v[24:25], off offset:2048
	v_add_co_u32_e32 v32, vcc, 0x1000, v24
	s_mov_b64 s[26:27], 0x1800
	v_lshl_add_u64 v[28:29], v[24:25], 0, s[54:55]
	v_lshl_add_u64 v[36:37], v[24:25], 0, s[26:27]
	v_addc_co_u32_e32 v33, vcc, 0, v25, vcc
	global_load_dwordx4 v[16:19], v[20:21], off offset:16
	s_nop 0
	global_load_dwordx4 v[20:23], v[20:21], off
	s_nop 0
	global_load_dwordx4 v[24:27], v[32:33], off
	s_nop 0
	global_load_dwordx4 v[28:31], v[28:29], off offset:16
	s_nop 0
	global_load_dwordx4 v[32:35], v[32:33], off offset:2048
	s_nop 0
	global_load_dwordx4 v[36:39], v[36:37], off offset:16
	v_mov_b32_e32 v175, v99
	v_lshl_add_u64 v[72:73], v[44:45], 0, v[174:175]
	v_lshl_add_u64 v[76:77], v[156:157], 0, s[20:21]
	v_lshl_add_u64 v[104:105], v[76:77], 0, v[172:173]
	v_lshl_add_u64 v[108:109], v[76:77], 0, v[174:175]
	s_lshl_b32 s1, s0, 6
	s_lshr_b32 s0, s23, 5
	s_ashr_i32 s72, s23, 8
	s_and_b32 s20, s23, 31
	s_cmp_eq_u32 s20, 0
	global_load_dword v41, v[68:69], off offset:768
	global_load_dword v252, v[68:69], off offset:512
	global_load_dword v42, v[68:69], off offset:1280
	global_load_dword v253, v[68:69], off offset:1024
	global_load_dword v43, v[68:69], off offset:1792
	global_load_dword v230, v[68:69], off offset:1536
	global_load_dword v44, v[72:73], off offset:256
	global_load_dword v231, v[72:73], off
	global_load_dword v45, v[72:73], off offset:768
	global_load_dword v232, v[72:73], off offset:512
	global_load_dword v46, v[72:73], off offset:1280
	global_load_dword v233, v[72:73], off offset:1024
	global_load_dword v47, v[72:73], off offset:1792
	global_load_dword v234, v[72:73], off offset:1536
	global_load_dword v48, v[68:69], off offset:320
	global_load_dword v235, v[68:69], off offset:64
	global_load_dword v49, v[68:69], off offset:832
	global_load_dword v120, v[68:69], off offset:576
	global_load_dword v50, v[68:69], off offset:1344
	global_load_dword v121, v[68:69], off offset:1088
	global_load_dword v51, v[68:69], off offset:1856
	global_load_dword v122, v[68:69], off offset:1600
	global_load_dword v52, v[72:73], off offset:320
	global_load_dword v123, v[72:73], off offset:64
	global_load_dword v53, v[72:73], off offset:832
	global_load_dword v143, v[72:73], off offset:576
	global_load_dword v54, v[72:73], off offset:1344
	global_load_dword v144, v[72:73], off offset:1088
	global_load_dword v55, v[72:73], off offset:1856
	global_load_dword v137, v[72:73], off offset:1600
	global_load_dword v56, v[68:69], off offset:384
	global_load_dword v138, v[68:69], off offset:128
	global_load_dword v57, v[68:69], off offset:896
	global_load_dword v139, v[68:69], off offset:640
	global_load_dword v58, v[68:69], off offset:1408
	global_load_dword v140, v[68:69], off offset:1152
	global_load_dword v59, v[68:69], off offset:1920
	global_load_dword v141, v[68:69], off offset:1664
	global_load_dword v60, v[72:73], off offset:384
	global_load_dword v142, v[72:73], off offset:128
	global_load_dword v61, v[72:73], off offset:896
	global_load_dword v133, v[72:73], off offset:640
	global_load_dword v62, v[72:73], off offset:1408
	global_load_dword v134, v[72:73], off offset:1152
	global_load_dword v63, v[72:73], off offset:1920
	global_load_dword v135, v[72:73], off offset:1664
	global_load_dword v64, v[68:69], off offset:448
	global_load_dword v136, v[68:69], off offset:192
	global_load_dword v65, v[68:69], off offset:960
	global_load_dword v239, v[68:69], off offset:704
	global_load_dword v66, v[68:69], off offset:1472
	global_load_dword v240, v[68:69], off offset:1216
	global_load_dword v67, v[68:69], off offset:1984
	s_nop 0
	global_load_dword v149, v[68:69], off offset:1728
	global_load_dword v68, v[72:73], off offset:448
	global_load_dword v150, v[72:73], off offset:192
	global_load_dword v69, v[72:73], off offset:960
	global_load_dword v151, v[72:73], off offset:704
	global_load_dword v70, v[72:73], off offset:1472
	global_load_dword v236, v[72:73], off offset:1216
	global_load_dword v71, v[72:73], off offset:1984
	s_nop 0
	global_load_dword v237, v[72:73], off offset:1728
	global_load_dword v72, v[104:105], off offset:256
	global_load_dword v238, v[104:105], off
	global_load_dword v73, v[104:105], off offset:768
	global_load_dword v145, v[104:105], off offset:512
	global_load_dword v74, v[104:105], off offset:1280
	global_load_dword v146, v[104:105], off offset:1024
	global_load_dword v75, v[104:105], off offset:1792
	global_load_dword v147, v[104:105], off offset:1536
	global_load_dword v76, v[108:109], off offset:256
	global_load_dword v148, v[108:109], off
	global_load_dword v77, v[108:109], off offset:768
	global_load_dword v111, v[108:109], off offset:512
	global_load_dword v78, v[108:109], off offset:1280
	global_load_dword v112, v[108:109], off offset:1024
	global_load_dword v79, v[108:109], off offset:1792
	global_load_dword v113, v[108:109], off offset:1536
	global_load_dword v80, v[104:105], off offset:320
	global_load_dword v114, v[104:105], off offset:64
	global_load_dword v81, v[104:105], off offset:832
	global_load_dword v115, v[104:105], off offset:576
	global_load_dword v82, v[104:105], off offset:1344
	global_load_dword v116, v[104:105], off offset:1088
	global_load_dword v83, v[104:105], off offset:1856
	global_load_dword v117, v[104:105], off offset:1600
	global_load_dword v84, v[108:109], off offset:320
	global_load_dword v118, v[108:109], off offset:64
	global_load_dword v85, v[108:109], off offset:832
	global_load_dword v119, v[108:109], off offset:576
	global_load_dword v86, v[108:109], off offset:1344
	global_load_dword v124, v[108:109], off offset:1088
	global_load_dword v87, v[108:109], off offset:1856
	global_load_dword v125, v[108:109], off offset:1600
	global_load_dword v88, v[104:105], off offset:384
	global_load_dword v126, v[104:105], off offset:128
	global_load_dword v89, v[104:105], off offset:896
	global_load_dword v127, v[104:105], off offset:640
	global_load_dword v90, v[104:105], off offset:1408
	global_load_dword v128, v[104:105], off offset:1152
	global_load_dword v91, v[104:105], off offset:1920
	global_load_dword v129, v[104:105], off offset:1664
	global_load_dword v92, v[108:109], off offset:384
	global_load_dword v130, v[108:109], off offset:128
	global_load_dword v93, v[108:109], off offset:896
	global_load_dword v131, v[108:109], off offset:640
	global_load_dword v94, v[108:109], off offset:1408
	global_load_dword v132, v[108:109], off offset:1152
	global_load_dword v95, v[108:109], off offset:1920
	global_load_dword v241, v[108:109], off offset:1664
	global_load_dword v100, v[104:105], off offset:448
	global_load_dword v242, v[104:105], off offset:192
	global_load_dword v101, v[104:105], off offset:960
	global_load_dword v243, v[104:105], off offset:704
	global_load_dword v102, v[104:105], off offset:1472
	global_load_dword v244, v[104:105], off offset:1216
	global_load_dword v103, v[104:105], off offset:1984
	s_nop 0
	global_load_dword v245, v[104:105], off offset:1728
	global_load_dword v104, v[108:109], off offset:448
	global_load_dword v246, v[108:109], off offset:192
	global_load_dword v105, v[108:109], off offset:960
	global_load_dword v247, v[108:109], off offset:704
	global_load_dword v106, v[108:109], off offset:1472
	global_load_dword v248, v[108:109], off offset:1216
	global_load_dword v107, v[108:109], off offset:1984
	s_nop 0
	global_load_dword v249, v[108:109], off offset:1728
	v_or_b32_e32 v109, s1, v220
	v_lshlrev_b32_e32 v109, 2, v109
	s_waitcnt vmcnt(0)
	v_cvt_pk_bf16_f32 v40, v251, v40
	v_cvt_pk_bf16_f32 v41, v252, v41
	v_cvt_pk_bf16_f32 v42, v253, v42
	v_cvt_pk_bf16_f32 v43, v230, v43
	v_cvt_pk_bf16_f32 v44, v231, v44
	v_cvt_pk_bf16_f32 v45, v232, v45
	v_cvt_pk_bf16_f32 v46, v233, v46
	v_cvt_pk_bf16_f32 v47, v234, v47
	v_cvt_pk_bf16_f32 v48, v235, v48
	v_cvt_pk_bf16_f32 v49, v120, v49
	v_cvt_pk_bf16_f32 v50, v121, v50
	v_cvt_pk_bf16_f32 v51, v122, v51
	v_cvt_pk_bf16_f32 v52, v123, v52
	v_cvt_pk_bf16_f32 v53, v143, v53
	v_cvt_pk_bf16_f32 v54, v144, v54
	v_cvt_pk_bf16_f32 v55, v137, v55
	v_cvt_pk_bf16_f32 v56, v138, v56
	v_cvt_pk_bf16_f32 v57, v139, v57
	v_cvt_pk_bf16_f32 v58, v140, v58
	v_cvt_pk_bf16_f32 v59, v141, v59
	v_cvt_pk_bf16_f32 v60, v142, v60
	v_cvt_pk_bf16_f32 v61, v133, v61
	v_cvt_pk_bf16_f32 v62, v134, v62
	v_cvt_pk_bf16_f32 v63, v135, v63
	v_cvt_pk_bf16_f32 v64, v136, v64
	v_cvt_pk_bf16_f32 v65, v239, v65
	v_cvt_pk_bf16_f32 v66, v240, v66
	v_cvt_pk_bf16_f32 v67, v149, v67
	v_cvt_pk_bf16_f32 v68, v150, v68
	v_cvt_pk_bf16_f32 v69, v151, v69
	v_cvt_pk_bf16_f32 v70, v236, v70
	v_cvt_pk_bf16_f32 v71, v237, v71
	v_cvt_pk_bf16_f32 v72, v238, v72
	v_cvt_pk_bf16_f32 v73, v145, v73
	v_cvt_pk_bf16_f32 v74, v146, v74
	v_cvt_pk_bf16_f32 v75, v147, v75
	v_cvt_pk_bf16_f32 v76, v148, v76
	v_cvt_pk_bf16_f32 v77, v111, v77
	v_cvt_pk_bf16_f32 v78, v112, v78
	v_cvt_pk_bf16_f32 v79, v113, v79
	v_cvt_pk_bf16_f32 v80, v114, v80
	v_cvt_pk_bf16_f32 v81, v115, v81
	v_cvt_pk_bf16_f32 v82, v116, v82
	v_cvt_pk_bf16_f32 v83, v117, v83
	v_cvt_pk_bf16_f32 v84, v118, v84
	v_cvt_pk_bf16_f32 v85, v119, v85
	v_cvt_pk_bf16_f32 v86, v124, v86
	v_cvt_pk_bf16_f32 v87, v125, v87
	v_cvt_pk_bf16_f32 v88, v126, v88
	v_cvt_pk_bf16_f32 v89, v127, v89
	v_cvt_pk_bf16_f32 v90, v128, v90
	v_cvt_pk_bf16_f32 v91, v129, v91
	v_cvt_pk_bf16_f32 v92, v130, v92
	v_cvt_pk_bf16_f32 v93, v131, v93
	v_cvt_pk_bf16_f32 v94, v132, v94
	v_cvt_pk_bf16_f32 v95, v241, v95
	v_cvt_pk_bf16_f32 v100, v242, v100
	v_cvt_pk_bf16_f32 v101, v243, v101
	v_cvt_pk_bf16_f32 v102, v244, v102
	v_cvt_pk_bf16_f32 v103, v245, v103
	v_cvt_pk_bf16_f32 v104, v246, v104
	v_cvt_pk_bf16_f32 v105, v247, v105
	v_cvt_pk_bf16_f32 v106, v248, v106
	v_cvt_pk_bf16_f32 v107, v249, v107
	global_load_dword v173, v109, s[8:9]
	global_load_dword v175, v109, s[68:69]
	global_load_dword v230, v109, s[8:9] offset:64
	global_load_dword v231, v109, s[68:69] offset:64
	global_load_dword v232, v109, s[8:9] offset:128
	global_load_dword v233, v109, s[68:69] offset:128
	global_load_dword v234, v109, s[68:69] offset:192
	global_load_dword v235, v109, s[8:9] offset:192
	global_load_dword v123, v109, s[70:71]
	global_load_dword v122, v109, s[70:71] offset:64
	global_load_dword v121, v109, s[70:71] offset:128
	global_load_dword v120, v109, s[70:71] offset:192
	s_cbranch_scc1 .LBB0_267
	s_and_b32 s26, s0, 7
	s_lshl_b32 s27, s72, 3
	s_or_b32 s26, s27, s26
	s_ashr_i32 s27, s26, 31
	s_lshl_b64 s[26:27], s[26:27], 14
	v_lshl_add_u64 v[108:109], v[164:165], 0, s[26:27]
	s_mov_b32 s26, 0
	v_mov_b32_e32 v177, 0
	s_branch .LBB0_253
